# low-rank (decay/iclr/gate) GEMM: K loop restricted to the two non-zero 64-wide K tiles of its block-structured weight per column tile (bit-identical)
# speedup vs baseline: 1.0811x; 1.0044x over previous
; #define PG8_STAGE(bufoff, gbase, voff) do { _Pragma("unroll") for (int _i = 0; _i < 2; ++_i) \
;         __builtin_amdgcn_global_load_lds((const unsigned*)((const char*)(gbase) + (voff)[_i]), (LAS unsigned*)(lds + (bufoff) + ldsw + _i * 8192), 16, 0, 0); } while (0)
; #define PG8_WAIT_V(n) asm volatile("s_waitcnt vmcnt(" #n ")" ::: "memory")
; #define PG8_BAR __builtin_amdgcn_s_barrier()
; template <class Epi>
; __device__ __forceinline__ void gemm_phase(LAS unsigned char* lds, const Gemm g, const Epi& E) {
;     ...
;     for (int i = 0; i < 2; ++i) { int R, C; stage_rc(tid * 16 + i * 8192, R, C); const int Ra = (g.ovl == 1) ? (R >> 6) * 62 + (R & 63) : R;
;         const int Rb = g.perm ? ((R & ~31) + 8 * ((R & 15) >> 2) + 4 * ((R >> 4) & 1) + (R & 3)) : R;
;         voffA[i] = (unsigned)(Ra * g.lda + C) * 2u; voffB[i] = (unsigned)(Rb * g.ldb + C) * 2u; }
;     const size_t kstep = (size_t)(BK * 2);
;     const size_t hstepA = (size_t)((g.ovl == 1) ? 124 : HALF) * g.lda * 2, hstepB = (size_t)HALF * g.ldb * 2;
;     ...
;     const char* cA = (const char*)g.A + (size_t)cur.pm * tstepA; const char* cB = (const char*)g.Bt + (size_t)cur.pn * tstepB;
;     PG8_STAGE(PG8_SB(0, 0), cB, voffB); PG8_STAGE(PG8_SA(0, 0), cA, voffA); PG8_STAGE(PG8_SB(0, 1), cB + hstepB, voffB); PG8_STAGE(PG8_SA(0, 1), cA + hstepA, voffA);
;     if (wr == 1) PG8_BAR;
;     PG8_WAIT_V(4); PG8_BAR;
;     PG8_STAGE(PG8_SB(1, 0), cB + kstep, voffB); PG8_STAGE(PG8_SA(1, 0), cA + kstep, voffA); PG8_STAGE(PG8_SB(1, 1), cB + hstepB + kstep, voffB);
.LBB0_262:
	v_lshlrev_b32_e32 v10, 6, v10
	v_mul_i32_i24_e32 v5, 64, v5
	v_lshlrev_b32_e32 v7, 5, v7
	v_sub_u32_e32 v8, v8, v10
	v_lshlrev_b32_e32 v2, 5, v2
	v_sub_u32_e32 v3, v3, v5
	v_and_b32_e32 v7, 32, v7
	v_ashrrev_i16_sdwa v8, v185, sext(v8) dst_sel:DWORD dst_unused:UNUSED_PAD src0_sel:DWORD src1_sel:BYTE_0
	v_and_b32_e32 v2, 32, v2
	v_ashrrev_i16_sdwa v3, v185, sext(v3) dst_sel:DWORD dst_unused:UNUSED_PAD src0_sel:DWORD src1_sel:BYTE_0
	v_add_u32_sdwa v7, v7, sext(v8) dst_sel:DWORD dst_unused:UNUSED_PAD src0_sel:DWORD src1_sel:WORD_0
	v_lshrrev_b32_e32 v8, 6, v9
	v_and_b32_e32 v10, 63, v9
	v_add_u32_sdwa v2, v2, sext(v3) dst_sel:DWORD dst_unused:UNUSED_PAD src0_sel:DWORD src1_sel:WORD_0
	v_lshrrev_b32_e32 v3, 6, v4
	v_and_b32_e32 v5, 63, v4
	v_mad_i32_i24 v8, v8, 62, v10
	s_mul_i32 s8, s4, s2
	s_mov_b32 s9, s29
	v_mad_i32_i24 v3, v3, 62, v5
	v_cndmask_b32_e64 v8, v9, v8, s[0:1]
	s_lshl_b64 s[26:27], s[8:9], 2
	v_cndmask_b32_e64 v3, v4, v3, s[0:1]
	s_ashr_i32 s0, s61, 31
	s_mul_i32 s0, s26, s0
	s_mul_hi_u32 s1, s26, s61
	s_add_i32 s0, s1, s0
	s_lshr_b32 s1, s8, 30
	v_mul_lo_u32 v8, v8, s2
	v_mul_lo_u32 v3, v3, s2
	s_mul_i32 s1, s1, s61
	v_add_lshl_u32 v164, v8, v7, 1
	v_mul_lo_u32 v8, v11, s2
	s_lshl_b32 s49, s2, 8
	s_lshl_b32 s6, s2, 9
	v_add_lshl_u32 v168, v3, v2, 1
	v_mul_lo_u32 v3, v6, s2
	s_add_i32 s2, s0, s1
	s_ashr_i32 s0, s44, 31
	s_ashr_i32 s12, s17, 6
	s_mul_i32 s0, s6, s0
	s_mul_hi_u32 s1, s6, s44
	s_ashr_i32 s5, s17, 8
	s_lshl_b64 s[34:35], s[8:9], 1
	s_lshl_b32 s7, s12, 10
	s_add_i32 s1, s1, s0
	s_mul_i32 s0, s6, s44
	s_add_u32 s0, s94, s0
	s_addc_u32 s1, s95, s1
	s_lshr_b32 s98, s44, 2
	s_lshl_b32 s98, s98, 8
	s_cmp_eq_u32 s53, 3
	s_cselect_b32 s98, s98, 0
	s_add_u32 s0, s0, s98
	s_addc_u32 s1, s1, 0
	s_add_i32 s8, s7, 0
	v_add_lshl_u32 v170, v3, v2, 1
	s_add_i32 m0, s8, 0x10000
	s_mul_i32 s4, s26, s61
	global_load_lds_dwordx4 v170, s[0:1]
	s_add_i32 m0, s8, 0x12000
	v_add_lshl_u32 v166, v8, v7, 1
	s_add_u32 s14, s96, s4
	v_writelane_b32 v249, s20, 56
	global_load_lds_dwordx4 v166, s[0:1]
	s_addc_u32 s15, s97, s2
	s_add_u32 s14, s14, s98
	s_addc_u32 s15, s15, 0
	s_mov_b32 m0, s8
	s_add_i32 s9, s8, 0x2000
	v_writelane_b32 v249, s21, 57
	global_load_lds_dwordx4 v168, s[14:15]
	s_mov_b32 m0, s9
	s_add_u32 s16, s0, s49
	v_writelane_b32 v249, s17, 58
	global_load_lds_dwordx4 v164, s[14:15]
	s_addc_u32 s17, s1, 0
	s_add_i32 m0, s8, 0x14000
	v_mov_b32_e32 v171, v1
	global_load_lds_dwordx4 v170, s[16:17]
	s_add_i32 m0, s8, 0x16000
	s_add_u32 s18, s14, s34
	s_addc_u32 s19, s15, s35
	s_add_i32 s2, s8, 0x4000
	global_load_lds_dwordx4 v166, s[16:17]
	s_mov_b32 m0, s2
	s_add_i32 s86, s8, 0x6000
	global_load_lds_dwordx4 v168, s[18:19]
	s_mov_b32 m0, s86
	v_mov_b32_e32 v167, v1
	global_load_lds_dwordx4 v164, s[18:19]
	v_mov_b32_e32 v169, v1
	v_mov_b32_e32 v165, v1
	v_lshl_add_u64 v[12:13], s[0:1], 0, v[170:171]
	v_lshl_add_u64 v[10:11], s[0:1], 0, v[166:167]
	v_lshl_add_u64 v[8:9], s[14:15], 0, v[168:169]
	v_lshl_add_u64 v[6:7], s[14:15], 0, v[164:165]
	v_lshl_add_u64 v[4:5], s[16:17], 0, v[170:171]
	s_cmp_lg_u32 s5, 1
	v_lshl_add_u64 v[2:3], s[16:17], 0, v[166:167]
	s_cbranch_scc1 .LBB0_264
	s_barrier
; __device__ __forceinline__ int o_tid() { int t = threadIdx.x; asm volatile("" : "+v"(t)); return t; }
; __device__ __forceinline__ int o_bid() { int t = blockIdx.x; asm volatile("" : "+s"(t)); return t; }
; template <class Epi>
; __device__ __forceinline__ void gemm_phase(LAS unsigned char* lds, const Gemm g, const Epi& E) {
;     const int tid = o_tid(), wid = __builtin_amdgcn_readfirstlane(tid >> 6), lane = tid & 63, wr = wid >> 2, wc = wid & 3, fr = lane & 15, fq = lane >> 4;
;     const int K = g.K, nt = K / BK;
;     StaticOrder S; S.init(g.nM, g.N, o_nblk(), o_bid());
;     unsigned voffA[2], voffB[2];
; #pragma unroll
;     for (int i = 0; i < 2; ++i) { int R, C; stage_rc(tid * 16 + i * 8192, R, C); const int Ra = (g.ovl == 1) ? (R >> 6) * 62 + (R & 63) : R;
;         const int Rb = g.perm ? ((R & ~31) + 8 * ((R & 15) >> 2) + 4 * ((R >> 4) & 1) + (R & 3)) : R;
;         voffA[i] = (unsigned)(Ra * g.lda + C) * 2u; voffB[i] = (unsigned)(Rb * g.ldb + C) * 2u; }
;     const size_t kstep = (size_t)(BK * 2);
;     const size_t hstepA = (size_t)((g.ovl == 1) ? 124 : HALF) * g.lda * 2, hstepB = (size_t)HALF * g.ldb * 2;
;     const size_t tstepA = 2 * hstepA, tstepB = 2 * hstepB;
;     const unsigned ldsw = (unsigned)wid * 1024u;
;     const int aoff = lds_byte(wr * 64 + fr, fq * 8), boff = lds_byte(wc * 32 + fr, fq * 8);
;     ...
;     const bool split = (g.ovl == 2); const size_t koff = (size_t)g.K * 2;
;     Unit cur, nxt; int ui = 0, chalf = 0, nhalf = 0;
;     if (!S.next(0, cur)) return;
;     f32x4 acc[2][2][4][2];
; #pragma unroll
;     for (int a = 0; a < 2; ++a)
; #pragma unroll
;         for (int b = 0; b < 2; ++b)
; #pragma unroll
;             for (int m = 0; m < 4; ++m)
; #pragma unroll
;                 for (int n = 0; n < 2; ++n) acc[a][b][m][n] = (f32x4){0.f, 0.f, 0.f, 0.f};
;     bf16x8 At[4][2], B0[2][2], B1[2][2];
;     const char* cA = (const char*)g.A + (size_t)cur.pm * tstepA; const char* cB = (const char*)g.Bt + (size_t)cur.pn * tstepB;
;     PG8_STAGE(PG8_SB(0, 0), cB, voffB); PG8_STAGE(PG8_SA(0, 0), cA, voffA); PG8_STAGE(PG8_SB(0, 1), cB + hstepB, voffB); PG8_STAGE(PG8_SA(0, 1), cA + hstepA, voffA);
;     if (wr == 1) PG8_BAR;
;     PG8_WAIT_V(4); PG8_BAR;
;     PG8_STAGE(PG8_SB(1, 0), cB + kstep, voffB); PG8_STAGE(PG8_SA(1, 0), cA + kstep, voffA); PG8_STAGE(PG8_SB(1, 1), cB + hstepB + kstep, voffB);
;     PG8_WAIT_V(6); PG8_BAR;
.LBB0_264:
	s_add_i32 m0, s8, 0x18000
	v_lshl_add_u64 v[12:13], v[12:13], 0, s[36:37]
	s_waitcnt vmcnt(4)
	s_barrier
	global_load_lds_dwordx4 v[12:13], off
	v_lshl_add_u64 v[10:11], v[10:11], 0, s[36:37]
	s_add_i32 m0, s8, 0x1a000
	s_add_i32 s38, s8, 0x8000
	global_load_lds_dwordx4 v[10:11], off
	v_lshl_add_u64 v[8:9], v[8:9], 0, s[36:37]
	s_mov_b32 m0, s38
	s_add_i32 s39, s8, 0xa000
	global_load_lds_dwordx4 v[8:9], off
	v_lshl_add_u64 v[6:7], v[6:7], 0, s[36:37]
	s_mov_b32 m0, s39
	v_lshl_add_u64 v[4:5], v[4:5], 0, s[36:37]
	global_load_lds_dwordx4 v[6:7], off
	s_add_i32 m0, s8, 0x1c000
	v_lshl_add_u64 v[2:3], v[2:3], 0, s[36:37]
	global_load_lds_dwordx4 v[4:5], off
	s_add_i32 m0, s8, 0x1e000
	v_bfe_u32 v14, v0, 4, 2
	global_load_lds_dwordx4 v[2:3], off
	v_and_b32_e32 v195, 15, v0
	v_lshlrev_b32_e32 v16, 4, v14
	v_lshlrev_b32_e32 v0, 2, v0
	s_and_b32 s4, s12, 3
	v_lshl_or_b32 v2, v195, 6, v16
	s_lshl_b32 s12, s5, 13
	v_and_b32_e32 v0, 32, v0
	v_bitop3_b32 v4, v2, s12, v0 bitop3:0xde
	s_lshl_b32 s12, s4, 12
	v_bitop3_b32 v197, v2, s12, v0 bitop3:0xde
	s_lshl_b32 s84, s10, 3
	v_lshlrev_b32_e32 v0, 2, v14
	v_lshl_or_b32 v199, s4, 4, v0
	v_cvt_f32_u32_e32 v0, s84
	s_lshr_b32 s87, s11, 6
	s_cmp_eq_u32 s53, 3
	s_cselect_b32 s87, 2, s87
	s_lshl_b32 s40, s11, 1
	s_lshr_b32 s11, s28, 3
	v_rcp_iflag_f32_e32 v0, v0
	v_lshl_or_b32 v196, s5, 6, v195
	v_lshlrev_b32_e32 v15, 3, v14
	v_writelane_b32 v249, s11, 59
	v_mul_f32_e32 v0, 0x4f7ffffe, v0
	v_cvt_u32_f32_e32 v0, v0
	s_mul_i32 s5, s5, 62
	v_writelane_b32 v249, s5, 60
	v_lshl_or_b32 v204, s4, 5, v15
	s_sub_i32 s4, 0, s84
	v_readfirstlane_b32 s5, v0
	s_waitcnt vmcnt(6)
	s_add_i32 s55, s11, 1
	v_cmp_ne_u32_e64 s[10:11], 0, v195
	s_mul_i32 s4, s4, s5
	v_mov_b32_e32 v2, v1
	v_mov_b32_e32 v3, v1
	v_cndmask_b32_e64 v198, 0, 1, s[92:93]
	v_writelane_b32 v249, s10, 61
	s_mul_hi_u32 s4, s5, s4
	v_mov_b32_e32 v0, v1
	v_add_u32_e32 v205, 0, v4
	v_mov_b64_e32 v[34:35], v[2:3]
	v_mov_b64_e32 v[30:31], v[2:3]
	v_mov_b64_e32 v[26:27], v[2:3]
	v_mov_b64_e32 v[22:23], v[2:3]
	v_mov_b64_e32 v[18:19], v[2:3]
	v_mov_b64_e32 v[14:15], v[2:3]
	v_mov_b64_e32 v[10:11], v[2:3]
	v_mov_b64_e32 v[6:7], v[2:3]
	v_mov_b64_e32 v[46:47], v[2:3]
	v_mov_b64_e32 v[42:43], v[2:3]
	v_mov_b64_e32 v[38:39], v[2:3]
	v_mov_b64_e32 v[130:131], v[2:3]
	v_mov_b64_e32 v[126:127], v[2:3]
	v_mov_b64_e32 v[122:123], v[2:3]
	v_mov_b64_e32 v[118:119], v[2:3]
	v_mov_b64_e32 v[114:115], v[2:3]
	v_mov_b64_e32 v[110:111], v[2:3]
	v_mov_b64_e32 v[106:107], v[2:3]
	v_mov_b64_e32 v[102:103], v[2:3]
	v_mov_b64_e32 v[98:99], v[2:3]
	v_mov_b64_e32 v[94:95], v[2:3]
	v_mov_b64_e32 v[90:91], v[2:3]
	v_mov_b64_e32 v[86:87], v[2:3]
	v_mov_b64_e32 v[82:83], v[2:3]
	v_mov_b64_e32 v[78:79], v[2:3]
	v_mov_b64_e32 v[74:75], v[2:3]
	v_mov_b64_e32 v[70:71], v[2:3]
	v_mov_b64_e32 v[66:67], v[2:3]
	v_mov_b64_e32 v[62:63], v[2:3]
	v_mov_b64_e32 v[58:59], v[2:3]
	v_mov_b64_e32 v[54:55], v[2:3]
	v_mov_b64_e32 v[50:51], v[2:3]
	s_ashr_i32 s41, s51, 31
	v_readfirstlane_b32 s42, v198
	s_ashr_i32 s43, s50, 31
	s_and_b32 s45, s28, 6
	s_add_i32 s85, s87, -2
	s_mov_b32 s16, 0
	v_writelane_b32 v249, s11, 62
	v_or_b32_e32 v200, 16, v195
	v_or_b32_e32 v201, 32, v195
	v_or_b32_e32 v202, 48, v195
	v_cmp_ne_u32_e64 s[10:11], 15, v195
	v_lshlrev_b32_e32 v203, 9, v196
	s_add_i32 s90, s5, s4
	v_lshl_add_u64 v[172:173], s[34:35], 0, v[164:165]
	v_lshl_add_u64 v[174:175], s[34:35], 0, v[168:169]
	v_mov_b64_e32 v[32:33], v[0:1]
	v_mov_b64_e32 v[28:29], v[0:1]
	v_mov_b64_e32 v[24:25], v[0:1]
	v_mov_b64_e32 v[20:21], v[0:1]
	v_mov_b64_e32 v[16:17], v[0:1]
	v_mov_b64_e32 v[12:13], v[0:1]
	v_mov_b64_e32 v[8:9], v[0:1]
	v_mov_b64_e32 v[4:5], v[0:1]
	v_mov_b64_e32 v[44:45], v[0:1]
	v_mov_b64_e32 v[40:41], v[0:1]
	v_mov_b64_e32 v[36:37], v[0:1]
	s_mov_b32 s91, 0
	v_mov_b64_e32 v[128:129], v[0:1]
	v_mov_b64_e32 v[124:125], v[0:1]
	v_mov_b64_e32 v[120:121], v[0:1]
	v_mov_b64_e32 v[116:117], v[0:1]
	v_mov_b64_e32 v[112:113], v[0:1]
	v_mov_b64_e32 v[108:109], v[0:1]
	v_mov_b64_e32 v[104:105], v[0:1]
	v_mov_b64_e32 v[100:101], v[0:1]
	v_mov_b64_e32 v[96:97], v[0:1]
	v_mov_b64_e32 v[92:93], v[0:1]
	v_mov_b64_e32 v[88:89], v[0:1]
	v_mov_b64_e32 v[84:85], v[0:1]
	v_mov_b64_e32 v[80:81], v[0:1]
	v_mov_b64_e32 v[76:77], v[0:1]
	v_mov_b64_e32 v[72:73], v[0:1]
	v_mov_b64_e32 v[68:69], v[0:1]
	v_mov_b64_e32 v[64:65], v[0:1]
	v_mov_b64_e32 v[60:61], v[0:1]
	v_mov_b64_e32 v[56:57], v[0:1]
	v_mov_b64_e32 v[52:53], v[0:1]
	v_mov_b64_e32 v[48:49], v[0:1]
	s_barrier
	v_writelane_b32 v249, s10, 63
	s_nop 1
	v_writelane_b32 v248, s11, 0
	s_branch .LBB0_267

; template <class Epi>
; __device__ __forceinline__ void gemm_phase(LAS unsigned char* lds, const Gemm g, const Epi& E) {
;     ...
;         const bool has_next = S.next(split ? ((ui + 1) >> 1) : (ui + 1), nxt);
;         const char* nA = has_next ? (const char*)g.A + (size_t)nxt.pm * tstepA + (nhalf ? koff : 0) : cA; const char* nB = has_next ? (const char*)g.Bt + (size_t)nxt.pn * tstepB + (nhalf ? koff : 0) : cB;
.LBB0_273:
	v_readfirstlane_b32 s4, v198
	v_cndmask_b32_e64 v0, 0, 1, s[12:13]
	s_and_b32 s31, s4, s91
	v_cmp_ne_u32_e64 s[10:11], 1, v0
	s_andn2_b64 vcc, exec, s[12:13]
	s_mov_b64 s[22:23], s[14:15]
	s_cbranch_vccnz .LBB0_275
	s_ashr_i32 s4, s30, 31
	s_mul_hi_u32 s5, s26, s30
	s_mul_i32 s4, s26, s4
	s_add_i32 s4, s5, s4
	s_mul_i32 s5, s27, s30
	s_add_i32 s4, s4, s5
	s_mul_i32 s5, s26, s30
	s_add_u32 s5, s96, s5
	s_addc_u32 s4, s97, s4
	s_cmp_lg_u32 s31, 0
	s_cselect_b32 s13, s40, 0
	s_cselect_b32 s12, 0, 0
	s_add_u32 s22, s5, s13
	s_addc_u32 s23, s4, s12
	s_lshr_b32 s99, s60, 2
	s_lshl_b32 s99, s99, 8
	s_cmp_eq_u32 s53, 3
	s_cselect_b32 s99, s99, 0
	s_add_u32 s22, s22, s99
	s_addc_u32 s23, s23, 0
.LBB0_275:
	s_and_b64 vcc, exec, s[10:11]
	s_mov_b64 s[4:5], s[0:1]
	s_cbranch_vccnz .LBB0_277
	s_ashr_i32 s4, s60, 31
	s_mul_hi_u32 s5, s6, s60
	s_mul_i32 s4, s6, s4
	s_add_i32 s5, s5, s4
	s_mul_i32 s4, s6, s60
	s_add_u32 s4, s94, s4
	s_addc_u32 s5, s95, s5
	s_cmp_lg_u32 s31, 0
	s_cselect_b32 s13, s40, 0
	s_cselect_b32 s12, 0, 0
	s_add_u32 s4, s4, s13
	s_addc_u32 s5, s5, s12
	s_lshr_b32 s99, s60, 2
	s_lshl_b32 s99, s99, 8
	s_cmp_eq_u32 s53, 3
	s_cselect_b32 s99, s99, 0
	s_add_u32 s4, s4, s99
	s_addc_u32 s5, s5, 0

; __global__ void __launch_bounds__(512, 2) fwd_megakernel(Params p, int ph_lo, int ph_hi) {
;     extern __shared__ __attribute__((aligned(16))) unsigned char shm[];
;     cg::grid_group grid = cg::this_grid();
;     unsigned nbar = 0;
;     for (int ph = ph_lo; ph < ph_hi; ++ph) {
;         KP kp = (KP)__builtin_amdgcn_kernarg_segment_ptr();
;         asm volatile("" : "+s"(kp));
;         run_phase(kp, ph, shm);
;         if (ph + 1 < ph_hi) {
;             if (ph == ph_lo) grid.sync();
;             else { ++nbar; fast_barrier((unsigned*)(kp->ws + OFF_BAR), nbar * gridDim.x); }
;         }
;     }
; }
	.amdhsa_kernel _Z14fwd_megakernel6Paramsii
		.amdhsa_group_segment_fixed_size 0
		.amdhsa_private_segment_fixed_size 0
		.amdhsa_kernarg_size 536
		.amdhsa_user_sgpr_count 2
		.amdhsa_user_sgpr_dispatch_ptr 0
		.amdhsa_user_sgpr_queue_ptr 0
		.amdhsa_user_sgpr_kernarg_segment_ptr 1
		.amdhsa_user_sgpr_dispatch_id 0
		.amdhsa_user_sgpr_kernarg_preload_length 0
		.amdhsa_user_sgpr_kernarg_preload_offset 0
		.amdhsa_user_sgpr_private_segment_size 0
		.amdhsa_uses_dynamic_stack 0
		.amdhsa_enable_private_segment 0
		.amdhsa_system_sgpr_workgroup_id_x 1
		.amdhsa_system_sgpr_workgroup_id_y 0
		.amdhsa_system_sgpr_workgroup_id_z 0
		.amdhsa_system_sgpr_workgroup_info 0
		.amdhsa_system_vgpr_workitem_id 2
		.amdhsa_next_free_vgpr 250
		.amdhsa_next_free_sgpr 102
		.amdhsa_accum_offset 252
		.amdhsa_reserve_vcc 1
		.amdhsa_float_round_mode_32 0
		.amdhsa_float_round_mode_16_64 0
		.amdhsa_float_denorm_mode_32 3
		.amdhsa_float_denorm_mode_16_64 3
		.amdhsa_dx10_clamp 1
		.amdhsa_ieee_mode 1
		.amdhsa_fp16_overflow 0
		.amdhsa_tg_split 0
		.amdhsa_exception_fp_ieee_invalid_op 0
		.amdhsa_exception_fp_denorm_src 0
		.amdhsa_exception_fp_ieee_div_zero 0
		.amdhsa_exception_fp_ieee_overflow 0
		.amdhsa_exception_fp_ieee_underflow 0
		.amdhsa_exception_fp_ieee_inexact 0
		.amdhsa_exception_int_div_zero 0
	.end_amdhsa_kernel

; __global__ void __launch_bounds__(512, 2) fwd_megakernel(Params p, int ph_lo, int ph_hi) {
;     extern __shared__ __attribute__((aligned(16))) unsigned char shm[];
;     cg::grid_group grid = cg::this_grid();
;     unsigned nbar = 0;
;     for (int ph = ph_lo; ph < ph_hi; ++ph) {
;         KP kp = (KP)__builtin_amdgcn_kernarg_segment_ptr();
;         asm volatile("" : "+s"(kp));
;         run_phase(kp, ph, shm);
;         if (ph + 1 < ph_hi) {
;             if (ph == ph_lo) grid.sync();
;             else { ++nbar; fast_barrier((unsigned*)(kp->ws + OFF_BAR), nbar * gridDim.x); }
;         }
;     }
; }
amdhsa.kernels:
  - .agpr_count:     0
    .args:
      - .offset:         0
        .size:           272
        .value_kind:     by_value
      - .offset:         272
        .size:           4
        .value_kind:     by_value
      - .offset:         276
        .size:           4
        .value_kind:     by_value
      - .offset:         280
        .size:           4
        .value_kind:     hidden_block_count_x
      - .offset:         284
        .size:           4
        .value_kind:     hidden_block_count_y
      - .offset:         288
        .size:           4
        .value_kind:     hidden_block_count_z
      - .offset:         292
        .size:           2
        .value_kind:     hidden_group_size_x
      - .offset:         294
        .size:           2
        .value_kind:     hidden_group_size_y
      - .offset:         296
        .size:           2
        .value_kind:     hidden_group_size_z
      - .offset:         298
        .size:           2
        .value_kind:     hidden_remainder_x
      - .offset:         300
        .size:           2
        .value_kind:     hidden_remainder_y
      - .offset:         302
        .size:           2
        .value_kind:     hidden_remainder_z
      - .offset:         320
        .size:           8
        .value_kind:     hidden_global_offset_x
      - .offset:         328
        .size:           8
        .value_kind:     hidden_global_offset_y
      - .offset:         336
        .size:           8
        .value_kind:     hidden_global_offset_z
      - .offset:         344
        .size:           2
        .value_kind:     hidden_grid_dims
      - .offset:         368
        .size:           8
        .value_kind:     hidden_multigrid_sync_arg
      - .offset:         400
        .size:           4
        .value_kind:     hidden_dynamic_lds_size
    .group_segment_fixed_size: 0
    .kernarg_segment_align: 8
    .kernarg_segment_size: 536
    .language:       OpenCL C
    .language_version:
      - 2
      - 0
    .max_flat_workgroup_size: 512
    .name:           _Z14fwd_megakernel6Paramsii
    .private_segment_fixed_size: 0
    .sgpr_count:     108
    .sgpr_spill_count: 65
    .symbol:         _Z14fwd_megakernel6Paramsii.kd
    .uniform_work_group_size: 1
    .uses_dynamic_stack: false
    .vgpr_count:     250
    .vgpr_spill_count: 0
    .wavefront_size: 64
